# v15: v10 + FoX hot loops: V fragments prefetched into free VGPRs, separate P quads, hoisted ones operand, permlane32 swap row max
# speedup vs baseline: 1.0059x; 1.0040x over previous
.LBB0_227:
	s_or_b64 exec, exec, s[30:31]
	s_waitcnt lgkmcnt(6)
	v_max_f32_e32 v6, v6, v6
	v_max_f32_e32 v0, v0, v0
	v_min_f32_e32 v0, v0, v6
	s_waitcnt lgkmcnt(4)
	v_min3_f32 v0, v0, v3, v4
	s_add_u32 s5, s5, s16
	s_waitcnt lgkmcnt(2)
	v_min3_f32 v0, v0, v5, v7
	s_addc_u32 s17, s22, 0
	s_waitcnt lgkmcnt(0)
	v_min3_f32 v3, v0, v8, v9
	s_add_u32 s30, s5, 0x1000
	v_ashrrev_i32_e32 v148, 3, v144
	v_readlane_b32 s5, v251, 12
	s_waitcnt vmcnt(0)
	v_cmp_ge_f32_e32 vcc, v2, v3
	s_addc_u32 s31, s17, 0
	v_add_u32_e32 v0, s5, v148
	s_movk_i32 s5, 0xa00
	v_mul_lo_u32 v0, v0, s5
	s_ff1_i32_b64 s5, vcc
	s_lshl_b32 s4, s4, 2
	s_min_u32 s74, s5, s4
	s_cmp_lg_u64 vcc, 0
	v_xor_b32_e32 v4, v148, v144
	s_cselect_b32 s17, s74, 0
	v_lshlrev_b32_e32 v4, 3, v4
	s_lshl_b32 s38, s17, 6
	s_mul_i32 s40, s17, 0x50000
	v_and_or_b32 v0, v4, 56, v0
	s_add_u32 s4, s84, s40
	s_addc_u32 s5, s85, 0
	v_lshlrev_b64 v[64:65], 1, v[0:1]
	s_waitcnt lgkmcnt(0)
	s_barrier
	v_lshl_add_u64 v[2:3], s[4:5], 0, v[64:65]
	s_mov_b64 s[78:79], 0xc00
	v_lshl_add_u64 v[2:3], v[2:3], 0, s[78:79]
	s_mov_b32 s4, m0
	s_mov_b32 m0, s0
	s_nop 0
	global_load_lds_dwordx4 v[2:3], off
	s_mov_b32 m0, s4
	s_add_u32 s4, s30, s40
	s_addc_u32 s5, s31, 0
	v_lshl_add_u64 v[2:3], s[4:5], 0, v[64:65]
	s_mov_b32 s4, m0
	s_mov_b32 m0, s27
	s_nop 0
	global_load_lds_dwordx4 v[2:3], off
	s_mov_b32 m0, s4
	s_lshl_b32 s36, s17, 8
	s_add_u32 s4, s28, s36
	v_ashrrev_i32_e32 v145, 31, v144
	s_addc_u32 s5, s29, 0
	v_lshlrev_b64 v[6:7], 2, v[144:145]
	v_lshl_add_u64 v[2:3], s[4:5], 0, v[6:7]
	s_add_i32 s26, s0, 0x18000
	s_mov_b32 s4, m0
	s_mov_b32 m0, s26
	s_nop 0
	global_load_lds_dword v[2:3], off
	s_mov_b32 m0, s4
	s_add_i32 s4, s38, 64
	s_add_i32 s22, s40, 0x50000
	s_mul_hi_u32 s39, s4, 0x1400
	s_add_u32 s4, s84, s22
	s_addc_u32 s5, s85, s39
	v_lshl_add_u64 v[4:5], s[4:5], 0, v[64:65]
	v_lshl_add_u64 v[4:5], v[4:5], 0, s[78:79]
	s_add_i32 s23, s0, 0x2000
	s_mov_b32 s4, m0
	s_mov_b32 m0, s23
	s_nop 0
	global_load_lds_dwordx4 v[4:5], off
	s_mov_b32 m0, s4
	s_add_u32 s4, s30, s22
	s_addc_u32 s5, s31, s39
	v_lshl_add_u64 v[4:5], s[4:5], 0, v[64:65]
	s_add_i32 s22, s0, 0xc000
	s_mov_b32 s4, m0
	s_mov_b32 m0, s22
	s_nop 0
	global_load_lds_dwordx4 v[4:5], off
	s_mov_b32 m0, s4
	v_lshl_add_u64 v[4:5], v[2:3], 0, s[24:25]
	s_add_i32 s39, s0, 0x18100
	s_mov_b32 s4, m0
	s_mov_b32 m0, s39
	s_nop 0
	global_load_lds_dword v[4:5], off
	s_mov_b32 m0, s4
	s_addk_i32 s38, 0x80
	s_add_i32 s40, s40, 0xa0000
	s_mul_hi_u32 s75, s38, 0x1400
	s_add_u32 s4, s84, s40
	s_addc_u32 s5, s85, s75
	v_lshl_add_u64 v[4:5], s[4:5], 0, v[64:65]
	v_lshl_add_u64 v[4:5], v[4:5], 0, s[78:79]
	s_add_i32 s38, s0, 0x4000
	s_mov_b32 s4, m0
	s_mov_b32 m0, s38
	s_nop 0
	global_load_lds_dwordx4 v[4:5], off
	s_mov_b32 m0, s4
	s_add_u32 s4, s30, s40
	s_addc_u32 s5, s31, s75
	v_lshl_add_u64 v[4:5], s[4:5], 0, v[64:65]
	s_add_i32 s5, s0, 0x10000
	s_mov_b32 s4, m0
	s_mov_b32 m0, s5
	s_nop 0
	global_load_lds_dwordx4 v[4:5], off
	s_mov_b32 m0, s4
	v_lshl_add_u64 v[2:3], v[2:3], 0, s[86:87]
	s_add_i32 s4, s0, 0x18200
	s_mov_b32 s40, m0
	s_mov_b32 m0, s4
	s_nop 0
	global_load_lds_dword v[2:3], off
	s_mov_b32 m0, s40
	v_lshlrev_b32_e32 v166, 4, v18
	v_readlane_b32 s40, v251, 14
	s_waitcnt vmcnt(3) lgkmcnt(0)
	s_barrier
	v_lshlrev_b32_e32 v167, 7, v149
	v_add_u32_e32 v72, 0, v167
	v_add_u32_e32 v0, s40, v166
	ds_read_b128 v[96:99], v0
	ds_read_b128 v[100:103], v0 offset:32
	ds_read_b128 v[104:107], v0 offset:64
	ds_read_b128 v[108:111], v0 offset:96
	v_bitop3_b32 v0, v18, v144, 7 bitop3:0x78
	v_lshlrev_b32_e32 v168, 4, v0
	v_add_u32_e32 v0, v72, v168
	ds_read_b128 v[2:5], v0
	v_add_u32_e32 v0, 2, v18
	v_bitop3_b32 v0, v0, v144, 7 bitop3:0x78
	v_lshlrev_b32_e32 v171, 4, v0
	v_add_u32_e32 v0, v72, v171
	s_waitcnt lgkmcnt(0)
	v_mfma_f32_32x32x16_bf16 v[96:111], v[2:5], v[140:143], v[96:111]
	ds_read_b128 v[2:5], v0
	v_add_u32_e32 v0, 4, v18
	v_bitop3_b32 v0, v0, v144, 7 bitop3:0x78
	v_lshlrev_b32_e32 v169, 4, v0
	v_add_u32_e32 v0, v72, v169
	v_bfe_u32 v163, v144, 2, 2
	s_lshr_b32 s40, s82, 6
	s_waitcnt lgkmcnt(0)
	v_mfma_f32_32x32x16_bf16 v[96:111], v[2:5], v[136:139], v[96:111]
	ds_read_b128 v[2:5], v0
	v_add_u32_e32 v0, 6, v18
	v_bitop3_b32 v0, v0, v144, 7 bitop3:0x78
	v_lshlrev_b32_e32 v170, 4, v0
	v_add_u32_e32 v0, v72, v170
	v_bfe_u32 v164, v144, 4, 1
	v_and_b32_e32 v165, 3, v144
	s_waitcnt lgkmcnt(0)
	v_mfma_f32_32x32x16_bf16 v[96:111], v[2:5], v[132:135], v[96:111]
	ds_read_b128 v[2:5], v0
	v_or_b32_e32 v162, v146, v163
	s_mov_b32 s83, 0
	s_mov_b64 s[86:87], 0xc00
	v_lshl_add_u64 v[152:153], s[30:31], 0, v[64:65]
	v_lshl_add_u64 v[154:155], s[28:29], 0, v[6:7]
	s_cmp_ge_u32 s17, s40
	s_waitcnt lgkmcnt(0)
	v_mfma_f32_32x32x16_bf16 v[96:111], v[2:5], v[128:131], v[96:111]
	v_lshl_add_u64 v[2:3], s[84:85], 0, v[64:65]
	v_lshl_add_u64 v[150:151], v[2:3], 0, s[78:79]
	s_cbranch_scc1 .LBB0_252
	v_lshlrev_b32_e32 v0, 1, v164
	v_lshrrev_b32_e32 v2, 1, v165
	v_or_b32_e32 v3, v0, v2
	v_bitop3_b32 v0, v0, v162, v2 bitop3:0x36
	v_lshlrev_b32_e32 v4, 3, v144
	v_lshlrev_b32_e32 v76, 4, v0
	v_bitop3_b32 v0, v3, v162, 4 bitop3:0x36
	v_lshl_add_u64 v[2:3], v[154:155], 0, s[36:37]
	s_mov_b64 s[78:79], 0x300
	v_and_b32_e32 v4, 8, v4
	v_lshl_add_u64 v[66:67], v[2:3], 0, s[78:79]
	v_mad_u64_u32 v[2:3], s[78:79], s17, v223, v[152:153]
	s_mov_b64 s[90:91], 0xf0000
	v_add_u32_e32 v4, 0, v4
	v_add_lshl_u32 v5, v146, v163, 7
	v_lshl_add_u64 v[68:69], v[2:3], 0, s[90:91]
	v_mad_u64_u32 v[2:3], s[78:79], s17, v223, v[150:151]
	v_mov_b32_e32 v14, v1
	v_mov_b32_e32 v15, v1
	v_readlane_b32 s77, v251, 13
	v_lshlrev_b32_e32 v77, 4, v0
	v_lshl_add_u32 v78, v162, 7, v4
	v_add3_u32 v79, v5, v4, s21
	v_lshl_add_u64 v[70:71], v[2:3], 0, s[90:91]
	v_mov_b32_e32 v0, v1
	v_mov_b32_e32 v2, v1
	v_mov_b32_e32 v3, v1
	v_mov_b32_e32 v4, v1
	v_mov_b32_e32 v5, v1
	v_mov_b32_e32 v6, v1
	v_mov_b32_e32 v7, v1
	v_mov_b32_e32 v8, v1
	v_mov_b32_e32 v9, v1
	v_mov_b32_e32 v10, v1
	v_mov_b32_e32 v11, v1
	v_mov_b32_e32 v12, v1
	v_mov_b32_e32 v13, v1
	v_mov_b64_e32 v[94:95], v[14:15]
	v_cmp_gt_u32_e64 s[74:75], 32, v144
	v_lshl_add_u32 v73, v149, 2, s77
	v_lshl_add_u32 v74, v146, 2, s77
	v_add_u32_e32 v75, s19, v166
	v_mov_b32_e32 v16, v1
	v_mov_b32_e32 v17, v1
	v_mov_b32_e32 v18, v1
	v_mov_b32_e32 v19, v1
	v_mov_b32_e32 v20, v1
	v_mov_b32_e32 v21, v1
	v_mov_b32_e32 v22, v1
	v_mov_b32_e32 v23, v1
	v_mov_b32_e32 v24, v1
	v_mov_b32_e32 v25, v1
	v_mov_b32_e32 v26, v1
	v_mov_b32_e32 v27, v1
	v_mov_b32_e32 v28, v1
	v_mov_b32_e32 v29, v1
	v_mov_b32_e32 v30, v1
	v_mov_b32_e32 v31, v1
	v_mov_b32_e32 v32, v1
	v_mov_b32_e32 v33, v1
	v_mov_b32_e32 v34, v1
	v_mov_b32_e32 v35, v1
	v_mov_b32_e32 v36, v1
	v_mov_b32_e32 v37, v1
	v_mov_b32_e32 v38, v1
	v_mov_b32_e32 v39, v1
	v_mov_b32_e32 v40, v1
	v_mov_b32_e32 v41, v1
	v_mov_b32_e32 v42, v1
	v_mov_b32_e32 v43, v1
	v_mov_b32_e32 v44, v1
	v_mov_b32_e32 v45, v1
	v_mov_b32_e32 v46, v1
	v_mov_b32_e32 v47, v1
	s_mov_b32 s36, 0
	v_mov_b32_e32 v172, 0xff800000
	v_mov_b64_e32 v[92:93], v[12:13]
	v_mov_b64_e32 v[90:91], v[10:11]
	v_mov_b64_e32 v[88:89], v[8:9]
	v_mov_b64_e32 v[86:87], v[6:7]
	v_mov_b64_e32 v[84:85], v[4:5]
	v_mov_b64_e32 v[82:83], v[2:3]
	v_mov_b64_e32 v[80:81], v[0:1]
	v_mov_b32_e32 v190, s76
	v_mov_b32_e32 v191, s76
	v_mov_b32_e32 v192, s76
	v_mov_b32_e32 v193, s76

.LBB0_231:
	v_lshl_add_u32 v0, s36, 13, v72
	s_or_b32 s77, s36, s95
	v_add_u32_e32 v2, v0, v168
	v_lshl_add_u32 v6, s77, 8, v75
	ds_read_b128 v[2:5], v2 offset:4096
	ds_read_b128 v[48:51], v6 offset:128
	ds_read_b128 v[52:55], v6 offset:160
	ds_read_b128 v[56:59], v6 offset:192
	ds_read_b128 v[60:63], v6 offset:224
	v_add_u32_e32 v6, v0, v171
	ds_read_b128 v[6:9], v6 offset:4096
	s_waitcnt lgkmcnt(1)
	v_mfma_f32_32x32x16_bf16 v[48:63], v[2:5], v[140:143], v[48:63]
	v_add_u32_e32 v2, v0, v169
	ds_read_b128 v[2:5], v2 offset:4096
	v_add_u32_e32 v0, v0, v170
	v_max_f32_e32 v10, v96, v96
	s_waitcnt lgkmcnt(1)
	v_mfma_f32_32x32x16_bf16 v[48:63], v[6:9], v[136:139], v[48:63]
	ds_read_b128 v[6:9], v0 offset:4096
	v_max_f32_e32 v0, v97, v97
	v_max_f32_e32 v0, v10, v0
	v_max3_f32 v0, v0, v98, v99
	v_max3_f32 v0, v0, v100, v101
	v_max3_f32 v0, v0, v102, v103
	v_max3_f32 v0, v0, v104, v105
	s_waitcnt lgkmcnt(1)
	v_mfma_f32_32x32x16_bf16 v[48:63], v[2:5], v[132:135], v[48:63]
	v_max3_f32 v0, v0, v106, v107
	v_max3_f32 v0, v0, v108, v109
	v_max3_f32 v0, v0, v110, v111
	v_mov_b32_e32 v2, v0
	s_nop 1
	v_permlane32_swap_b32_e32 v0, v2
	s_waitcnt lgkmcnt(0)
	v_max_f32_e32 v2, v2, v2
	v_mfma_f32_32x32x16_bf16 v[48:63], v[6:9], v[128:131], v[48:63]
	v_max_f32_e32 v0, v0, v2
	v_cmp_ge_f32_e32 vcc, v0, v161
	s_cbranch_vccz .LBB0_236
	v_add_f32_e32 v2, 0x41000000, v172
	v_cmp_gt_f32_e32 vcc, v0, v2
	s_cbranch_vccz .LBB0_237
	v_max_f32_e32 v0, v0, v0
	v_max_f32_e32 v2, v172, v172
	v_max_f32_e32 v0, v2, v0
	s_and_saveexec_b64 s[78:79], s[74:75]
	s_cbranch_execz .LBB0_235
	v_sub_f32_e32 v2, v172, v0
	v_exp_f32_e32 v2, v2
	ds_write_b32 v73, v2

.LBB0_238:
	v_lshl_add_u32 v235, s36, 14, v78
	v_add_u32_e32 v234, v235, v76
	v_add_u32_e32 v235, v235, v77
	ds_read_b64_tr_b16 v[174:175], v234 offset:32768
	ds_read_b64_tr_b16 v[176:177], v234 offset:33792
	ds_read_b64_tr_b16 v[178:179], v235 offset:32768
	ds_read_b64_tr_b16 v[180:181], v235 offset:33792
	ds_read_b64_tr_b16 v[182:183], v234 offset:34816
	ds_read_b64_tr_b16 v[184:185], v234 offset:35840
	ds_read_b64_tr_b16 v[186:187], v235 offset:34816
	ds_read_b64_tr_b16 v[188:189], v235 offset:35840
	v_sub_f32_e32 v96, v96, v0
	v_sub_f32_e32 v97, v97, v0
	v_sub_f32_e32 v98, v98, v0
	v_sub_f32_e32 v99, v99, v0
	v_sub_f32_e32 v100, v100, v0
	v_sub_f32_e32 v101, v101, v0
	v_sub_f32_e32 v102, v102, v0
	v_sub_f32_e32 v103, v103, v0
	v_exp_f32_e32 v96, v96
	v_exp_f32_e32 v97, v97
	v_exp_f32_e32 v98, v98
	v_exp_f32_e32 v99, v99
	v_exp_f32_e32 v100, v100
	v_exp_f32_e32 v101, v101
	v_exp_f32_e32 v102, v102
	v_exp_f32_e32 v103, v103
	v_cvt_pk_bf16_f32 v196, v96, v97
	v_cvt_pk_bf16_f32 v197, v98, v99
	v_cvt_pk_bf16_f32 v198, v100, v101
	v_cvt_pk_bf16_f32 v199, v102, v103
	v_sub_f32_e32 v104, v104, v0
	v_sub_f32_e32 v105, v105, v0
	v_sub_f32_e32 v106, v106, v0
	v_sub_f32_e32 v107, v107, v0
	v_sub_f32_e32 v108, v108, v0
	v_sub_f32_e32 v109, v109, v0
	v_sub_f32_e32 v110, v110, v0
	v_sub_f32_e32 v111, v111, v0
	s_mov_b32 s77, s76
	s_mov_b32 s78, s76
	s_mov_b32 s79, s76
	s_waitcnt lgkmcnt(6)
	v_mfma_f32_32x32x16_bf16 v[16:31], v[196:199], v[174:177], v[16:31]
	v_exp_f32_e32 v104, v104
	v_exp_f32_e32 v105, v105
	v_exp_f32_e32 v106, v106
	s_waitcnt lgkmcnt(4)
	v_mfma_f32_32x32x16_bf16 v[32:47], v[196:199], v[178:181], v[32:47]
	v_exp_f32_e32 v107, v107
	v_exp_f32_e32 v108, v108
	v_exp_f32_e32 v109, v109
	v_mfma_f32_32x32x16_bf16 v[80:95], v[196:199], v[190:193], v[80:95]
	v_exp_f32_e32 v110, v110
	v_exp_f32_e32 v111, v111
	v_cvt_pk_bf16_f32 v200, v104, v105
	v_cvt_pk_bf16_f32 v201, v106, v107
	v_cvt_pk_bf16_f32 v202, v108, v109
	v_cvt_pk_bf16_f32 v203, v110, v111
	s_nop 0
	s_waitcnt lgkmcnt(2)
	v_mfma_f32_32x32x16_bf16 v[16:31], v[200:203], v[182:185], v[16:31]
	s_waitcnt lgkmcnt(0)
	v_mfma_f32_32x32x16_bf16 v[32:47], v[200:203], v[186:189], v[32:47]
	v_mfma_f32_32x32x16_bf16 v[80:95], v[200:203], v[190:193], v[80:95]
.LBB0_239:
	s_add_i32 s77, s36, 1
	s_and_b32 s83, s77, 3
	v_lshl_add_u32 v10, s83, 13, v72
	s_or_b32 s77, s83, s95
	v_add_u32_e32 v2, v10, v168
	v_lshl_add_u32 v6, s77, 8, v75
	ds_read_b128 v[2:5], v2
	ds_read_b128 v[96:99], v6
	ds_read_b128 v[100:103], v6 offset:32
	ds_read_b128 v[104:107], v6 offset:64
	ds_read_b128 v[108:111], v6 offset:96
	v_add_u32_e32 v6, v10, v171
	ds_read_b128 v[6:9], v6
	s_waitcnt lgkmcnt(1)
	v_mfma_f32_32x32x16_bf16 v[96:111], v[2:5], v[140:143], v[96:111]
	v_add_u32_e32 v2, v10, v169
	ds_read_b128 v[2:5], v2
	v_max_f32_e32 v11, v48, v48
	s_waitcnt lgkmcnt(1)
	v_mfma_f32_32x32x16_bf16 v[96:111], v[6:9], v[136:139], v[96:111]
	v_add_u32_e32 v6, v10, v170
	ds_read_b128 v[6:9], v6
	v_max_f32_e32 v10, v49, v49
	v_max_f32_e32 v10, v11, v10
	v_max3_f32 v10, v10, v50, v51
	v_max3_f32 v10, v10, v52, v53
	s_waitcnt lgkmcnt(1)
	v_mfma_f32_32x32x16_bf16 v[96:111], v[2:5], v[132:135], v[96:111]
	v_max3_f32 v2, v10, v54, v55
	v_max3_f32 v2, v2, v56, v57
	v_max3_f32 v2, v2, v58, v59
	v_max3_f32 v2, v2, v60, v61
	v_max3_f32 v2, v2, v62, v63
	v_mov_b32_e32 v3, v2
	s_nop 1
	v_permlane32_swap_b32_e32 v2, v3
	s_waitcnt lgkmcnt(0)
	v_max_f32_e32 v3, v3, v3
	v_mfma_f32_32x32x16_bf16 v[96:111], v[6:9], v[128:131], v[96:111]
	v_max_f32_e32 v2, v2, v3
	v_cmp_ge_f32_e32 vcc, v2, v161
	s_cbranch_vccz .LBB0_244
	v_add_f32_e32 v3, 0x41000000, v0
	v_cmp_gt_f32_e32 vcc, v2, v3
	s_cbranch_vccz .LBB0_245
	v_max_f32_e32 v2, v2, v2
	v_max_f32_e32 v3, v0, v0
	v_max_f32_e32 v172, v3, v2
	s_and_saveexec_b64 s[78:79], s[74:75]
	s_cbranch_execz .LBB0_243
	v_sub_f32_e32 v0, v0, v172
	v_exp_f32_e32 v0, v0
	ds_write_b32 v73, v0

.LBB0_246:
	v_lshl_add_u32 v235, s36, 14, v79
	v_add_u32_e32 v234, v235, v76
	v_add_u32_e32 v235, v235, v77
	ds_read_b64_tr_b16 v[174:175], v234 offset:32768
	ds_read_b64_tr_b16 v[176:177], v234 offset:33792
	ds_read_b64_tr_b16 v[178:179], v235 offset:32768
	ds_read_b64_tr_b16 v[180:181], v235 offset:33792
	ds_read_b64_tr_b16 v[182:183], v234 offset:34816
	ds_read_b64_tr_b16 v[184:185], v234 offset:35840
	ds_read_b64_tr_b16 v[186:187], v235 offset:34816
	ds_read_b64_tr_b16 v[188:189], v235 offset:35840
	v_sub_f32_e32 v48, v48, v172
	v_sub_f32_e32 v49, v49, v172
	v_sub_f32_e32 v50, v50, v172
	v_sub_f32_e32 v51, v51, v172
	v_sub_f32_e32 v52, v52, v172
	v_sub_f32_e32 v53, v53, v172
	v_sub_f32_e32 v54, v54, v172
	v_sub_f32_e32 v55, v55, v172
	v_exp_f32_e32 v48, v48
	v_exp_f32_e32 v49, v49
	v_exp_f32_e32 v50, v50
	v_exp_f32_e32 v51, v51
	v_exp_f32_e32 v52, v52
	v_exp_f32_e32 v53, v53
	v_exp_f32_e32 v54, v54
	v_exp_f32_e32 v55, v55
	v_cvt_pk_bf16_f32 v196, v48, v49
	v_cvt_pk_bf16_f32 v197, v50, v51
	v_cvt_pk_bf16_f32 v198, v52, v53
	v_cvt_pk_bf16_f32 v199, v54, v55
	v_sub_f32_e32 v56, v56, v172
	v_sub_f32_e32 v57, v57, v172
	v_sub_f32_e32 v58, v58, v172
	v_sub_f32_e32 v59, v59, v172
	v_sub_f32_e32 v60, v60, v172
	v_sub_f32_e32 v61, v61, v172
	v_sub_f32_e32 v62, v62, v172
	v_sub_f32_e32 v63, v63, v172
	s_mov_b32 s77, s76
	s_mov_b32 s78, s76
	s_mov_b32 s79, s76
	s_waitcnt lgkmcnt(6)
	v_mfma_f32_32x32x16_bf16 v[16:31], v[196:199], v[174:177], v[16:31]
	v_exp_f32_e32 v56, v56
	v_exp_f32_e32 v57, v57
	v_exp_f32_e32 v58, v58
	s_waitcnt lgkmcnt(4)
	v_mfma_f32_32x32x16_bf16 v[32:47], v[196:199], v[178:181], v[32:47]
	v_exp_f32_e32 v59, v59
	v_exp_f32_e32 v60, v60
	v_exp_f32_e32 v61, v61
	v_mfma_f32_32x32x16_bf16 v[80:95], v[196:199], v[190:193], v[80:95]
	v_exp_f32_e32 v62, v62
	v_exp_f32_e32 v63, v63
	v_cvt_pk_bf16_f32 v200, v56, v57
	v_cvt_pk_bf16_f32 v201, v58, v59
	v_cvt_pk_bf16_f32 v202, v60, v61
	v_cvt_pk_bf16_f32 v203, v62, v63
	s_nop 0
	s_waitcnt lgkmcnt(2)
	v_mfma_f32_32x32x16_bf16 v[16:31], v[200:203], v[182:185], v[16:31]
	s_waitcnt lgkmcnt(0)
	v_mfma_f32_32x32x16_bf16 v[32:47], v[200:203], v[186:189], v[32:47]
	v_mfma_f32_32x32x16_bf16 v[80:95], v[200:203], v[190:193], v[80:95]
	s_movk_i32 s77, 0x110
	s_mov_b64 s[78:79], -1
	s_and_b64 vcc, exec, s[90:91]
	s_cbranch_vccz .LBB0_248

.LBB0_296:
	s_or_b64 exec, exec, s[74:75]
	s_waitcnt lgkmcnt(6)
	v_max_f32_e32 v6, v6, v6
	v_max_f32_e32 v0, v0, v0
	v_min_f32_e32 v0, v0, v6
	s_waitcnt lgkmcnt(4)
	v_min3_f32 v0, v0, v2, v4
	s_waitcnt lgkmcnt(2)
	v_min3_f32 v0, v0, v5, v7
	s_waitcnt lgkmcnt(0)
	v_min3_f32 v2, v0, v8, v9
	v_ashrrev_i32_e32 v146, 3, v144
	v_readlane_b32 s17, v251, 12
	s_waitcnt vmcnt(0)
	v_cmp_ge_f32_e32 vcc, v3, v2
	s_lshl_b32 s10, s10, 2
	v_add_u32_e32 v0, s17, v146
	s_movk_i32 s17, 0xa00
	v_mul_lo_u32 v0, v0, s17
	s_ff1_i32_b64 s17, vcc
	s_min_u32 s10, s17, s10
	s_cmp_lg_u64 vcc, 0
	v_xor_b32_e32 v4, v146, v144
	s_cselect_b32 s96, s10, 0
	v_lshlrev_b32_e32 v4, 3, v4
	s_lshl_b32 s10, s96, 6
	s_mul_i32 s17, s96, 0x50000
	v_and_or_b32 v0, v4, 56, v0
	s_add_u32 s74, s84, s17
	s_addc_u32 s75, s85, 0
	v_lshlrev_b64 v[64:65], 1, v[0:1]
	s_waitcnt lgkmcnt(0)
	s_barrier
	v_lshl_add_u64 v[2:3], s[74:75], 0, v[64:65]
	s_mov_b64 s[78:79], 0xc00
	s_add_u32 s74, s30, s17
	v_lshl_add_u64 v[2:3], v[2:3], 0, s[78:79]
	s_mov_b32 s36, m0
	s_mov_b32 m0, s0
	s_nop 0
	global_load_lds_dwordx4 v[2:3], off
	s_mov_b32 m0, s36
	s_addc_u32 s75, s31, 0
	v_lshl_add_u64 v[2:3], s[74:75], 0, v[64:65]
	s_mov_b32 s36, m0
	s_mov_b32 m0, s27
	s_nop 0
	global_load_lds_dwordx4 v[2:3], off
	s_mov_b32 m0, s36
	s_lshl_b32 s36, s96, 8
	s_add_u32 s74, s28, s36
	v_ashrrev_i32_e32 v145, 31, v144
	s_addc_u32 s75, s29, 0
	v_lshlrev_b64 v[6:7], 2, v[144:145]
	v_lshl_add_u64 v[2:3], s[74:75], 0, v[6:7]
	s_mov_b32 s40, m0
	s_mov_b32 m0, s26
	s_nop 0
	global_load_lds_dword v[2:3], off
	s_mov_b32 m0, s40
	s_add_i32 s26, s10, 64
	s_add_i32 s40, s17, 0x50000
	s_mul_hi_u32 s26, s26, 0x1400
	s_add_u32 s74, s84, s40
	s_addc_u32 s75, s85, s26
	v_lshl_add_u64 v[4:5], s[74:75], 0, v[64:65]
	v_lshl_add_u64 v[4:5], v[4:5], 0, s[78:79]
	s_mov_b32 s74, m0
	s_mov_b32 m0, s23
	s_nop 0
	global_load_lds_dwordx4 v[4:5], off
	s_mov_b32 m0, s74
	s_add_u32 s74, s30, s40
	s_addc_u32 s75, s31, s26
	v_lshl_add_u64 v[4:5], s[74:75], 0, v[64:65]
	s_mov_b32 s23, m0
	s_mov_b32 m0, s22
	s_nop 0
	global_load_lds_dwordx4 v[4:5], off
	s_mov_b32 m0, s23
	v_lshl_add_u64 v[4:5], v[2:3], 0, s[24:25]
	s_mov_b32 s22, m0
	s_mov_b32 m0, s39
	s_nop 0
	global_load_lds_dword v[4:5], off
	s_mov_b32 m0, s22
	s_addk_i32 s10, 0x80
	s_add_i32 s17, s17, 0xa0000
	s_mul_hi_u32 s10, s10, 0x1400
	s_add_u32 s22, s84, s17
	s_addc_u32 s23, s85, s10
	v_lshl_add_u64 v[4:5], s[22:23], 0, v[64:65]
	v_lshl_add_u64 v[4:5], v[4:5], 0, s[78:79]
	s_mov_b32 s22, m0
	s_mov_b32 m0, s38
	s_nop 0
	global_load_lds_dwordx4 v[4:5], off
	s_mov_b32 m0, s22
	s_add_u32 s22, s30, s17
	s_addc_u32 s23, s31, s10
	v_lshl_add_u64 v[4:5], s[22:23], 0, v[64:65]
	s_mov_b32 s10, m0
	s_mov_b32 m0, s5
	s_nop 0
	global_load_lds_dwordx4 v[4:5], off
	s_mov_b32 m0, s10
	v_lshl_add_u64 v[2:3], v[2:3], 0, s[86:87]
	s_mov_b32 s5, m0
	s_mov_b32 m0, s4
	s_nop 0
	global_load_lds_dword v[2:3], off
	s_mov_b32 m0, s5
	v_lshlrev_b32_e32 v164, 7, v161
	v_bitop3_b32 v2, v18, v144, 7 bitop3:0x78
	v_add_u32_e32 v72, 0, v164
	v_lshlrev_b32_e32 v165, 4, v2
	s_waitcnt vmcnt(3) lgkmcnt(0)
	s_barrier
	v_lshlrev_b32_e32 v159, 4, v18
	v_readlane_b32 s4, v251, 14
	v_add_u32_e32 v2, v72, v165
	v_bfe_u32 v156, v144, 2, 2
	v_add_u32_e32 v0, s4, v159
	ds_read_b128 v[2:5], v2
	ds_read_b128 v[96:99], v0
	ds_read_b128 v[100:103], v0 offset:32
	ds_read_b128 v[104:107], v0 offset:64
	ds_read_b128 v[108:111], v0 offset:96
	v_add_u32_e32 v0, 2, v18
	v_bitop3_b32 v0, v0, v144, 7 bitop3:0x78
	v_lshlrev_b32_e32 v166, 4, v0
	v_add_u32_e32 v0, v72, v166
	s_waitcnt lgkmcnt(0)
	v_mfma_f32_32x32x16_bf16 v[96:111], v[2:5], v[128:131], v[96:111]
	ds_read_b128 v[2:5], v0
	v_add_u32_e32 v0, 4, v18
	v_bitop3_b32 v0, v0, v144, 7 bitop3:0x78
	v_lshlrev_b32_e32 v160, 4, v0
	v_add_u32_e32 v0, v72, v160
	s_lshr_b32 s4, s82, 6
	v_bfe_u32 v157, v144, 4, 1
	s_waitcnt lgkmcnt(0)
	v_mfma_f32_32x32x16_bf16 v[96:111], v[2:5], v[140:143], v[96:111]
	ds_read_b128 v[2:5], v0
	v_add_u32_e32 v0, 6, v18
	v_bitop3_b32 v0, v0, v144, 7 bitop3:0x78
	v_lshlrev_b32_e32 v163, 4, v0
	v_add_u32_e32 v0, v72, v163
	v_and_b32_e32 v158, 3, v144
	v_or_b32_e32 v149, v148, v156
	s_waitcnt lgkmcnt(0)
	v_mfma_f32_32x32x16_bf16 v[96:111], v[2:5], v[136:139], v[96:111]
	ds_read_b128 v[2:5], v0
	s_mov_b32 s5, 0
	v_lshl_add_u64 v[152:153], s[30:31], 0, v[64:65]
	s_cmp_ge_u32 s96, s4
	v_lshl_add_u64 v[154:155], s[28:29], 0, v[6:7]
	s_waitcnt lgkmcnt(0)
	v_mfma_f32_32x32x16_bf16 v[96:111], v[2:5], v[132:135], v[96:111]
	v_lshl_add_u64 v[2:3], s[84:85], 0, v[64:65]
	v_lshl_add_u64 v[150:151], v[2:3], 0, s[78:79]
	s_cbranch_scc1 .LBB0_321
	v_lshlrev_b32_e32 v0, 1, v157
	v_lshrrev_b32_e32 v2, 1, v158
	v_or_b32_e32 v3, v0, v2
	v_bitop3_b32 v0, v0, v149, v2 bitop3:0x36
	v_lshlrev_b32_e32 v4, 3, v144
	v_lshlrev_b32_e32 v76, 4, v0
	v_bitop3_b32 v0, v3, v149, 4 bitop3:0x36
	v_lshl_add_u64 v[2:3], v[154:155], 0, s[36:37]
	s_mov_b64 s[22:23], 0x300
	v_and_b32_e32 v4, 8, v4
	v_lshl_add_u64 v[66:67], v[2:3], 0, s[22:23]
	v_mad_u64_u32 v[2:3], s[22:23], s96, v223, v[152:153]
	s_mov_b64 s[38:39], 0xf0000
	v_add_u32_e32 v4, 0, v4
	v_add_lshl_u32 v5, v148, v156, 7
	v_lshl_add_u64 v[68:69], v[2:3], 0, s[38:39]
	v_mad_u64_u32 v[2:3], s[22:23], s96, v223, v[150:151]
	v_mov_b32_e32 v14, v1
	v_mov_b32_e32 v15, v1
	v_readlane_b32 s5, v251, 13
	v_lshlrev_b32_e32 v77, 4, v0
	v_lshl_add_u32 v78, v149, 7, v4
	v_add3_u32 v79, v5, v4, s21
	v_lshl_add_u64 v[70:71], v[2:3], 0, s[38:39]
	v_mov_b32_e32 v0, v1
	v_mov_b32_e32 v2, v1
	v_mov_b32_e32 v3, v1
	v_mov_b32_e32 v4, v1
	v_mov_b32_e32 v5, v1
	v_mov_b32_e32 v6, v1
	v_mov_b32_e32 v7, v1
	v_mov_b32_e32 v8, v1
	v_mov_b32_e32 v9, v1
	v_mov_b32_e32 v10, v1
	v_mov_b32_e32 v11, v1
	v_mov_b32_e32 v12, v1
	v_mov_b32_e32 v13, v1
	v_mov_b64_e32 v[94:95], v[14:15]
	v_cmp_gt_u32_e64 s[74:75], 32, v144
	v_lshl_add_u32 v73, v161, 2, s5
	v_lshl_add_u32 v74, v148, 2, s5
	v_add_u32_e32 v75, s19, v159
	v_mov_b32_e32 v16, v1
	v_mov_b32_e32 v17, v1
	v_mov_b32_e32 v18, v1
	v_mov_b32_e32 v19, v1
	v_mov_b32_e32 v20, v1
	v_mov_b32_e32 v21, v1
	v_mov_b32_e32 v22, v1
	v_mov_b32_e32 v23, v1
	v_mov_b32_e32 v24, v1
	v_mov_b32_e32 v25, v1
	v_mov_b32_e32 v26, v1
	v_mov_b32_e32 v27, v1
	v_mov_b32_e32 v28, v1
	v_mov_b32_e32 v29, v1
	v_mov_b32_e32 v30, v1
	v_mov_b32_e32 v31, v1
	v_mov_b32_e32 v32, v1
	v_mov_b32_e32 v33, v1
	v_mov_b32_e32 v34, v1
	v_mov_b32_e32 v35, v1
	v_mov_b32_e32 v36, v1
	v_mov_b32_e32 v37, v1
	v_mov_b32_e32 v38, v1
	v_mov_b32_e32 v39, v1
	v_mov_b32_e32 v40, v1
	v_mov_b32_e32 v41, v1
	v_mov_b32_e32 v42, v1
	v_mov_b32_e32 v43, v1
	v_mov_b32_e32 v44, v1
	v_mov_b32_e32 v45, v1
	v_mov_b32_e32 v46, v1
	v_mov_b32_e32 v47, v1
	s_mov_b32 s17, 0
	v_mov_b32_e32 v167, 0xff800000
	v_mov_b64_e32 v[92:93], v[12:13]
	v_mov_b64_e32 v[90:91], v[10:11]
	v_mov_b64_e32 v[88:89], v[8:9]
	v_mov_b64_e32 v[86:87], v[6:7]
	v_mov_b64_e32 v[84:85], v[4:5]
	v_mov_b64_e32 v[82:83], v[2:3]
	v_mov_b64_e32 v[80:81], v[0:1]
	s_mov_b32 s10, s96
	v_mov_b32_e32 v190, s76
	v_mov_b32_e32 v191, s76
	v_mov_b32_e32 v192, s76
	v_mov_b32_e32 v193, s76

.LBB0_300:
	v_lshl_add_u32 v0, s17, 13, v72
	s_or_b32 s5, s17, s95
	v_add_u32_e32 v2, v0, v165
	v_lshl_add_u32 v6, s5, 8, v75
	ds_read_b128 v[2:5], v2 offset:4096
	ds_read_b128 v[48:51], v6 offset:128
	ds_read_b128 v[52:55], v6 offset:160
	ds_read_b128 v[56:59], v6 offset:192
	ds_read_b128 v[60:63], v6 offset:224
	v_add_u32_e32 v6, v0, v166
	ds_read_b128 v[6:9], v6 offset:4096
	s_waitcnt lgkmcnt(1)
	v_mfma_f32_32x32x16_bf16 v[48:63], v[2:5], v[128:131], v[48:63]
	v_add_u32_e32 v2, v0, v160
	ds_read_b128 v[2:5], v2 offset:4096
	v_add_u32_e32 v0, v0, v163
	v_max_f32_e32 v10, v96, v96
	s_waitcnt lgkmcnt(1)
	v_mfma_f32_32x32x16_bf16 v[48:63], v[6:9], v[140:143], v[48:63]
	ds_read_b128 v[6:9], v0 offset:4096
	v_max_f32_e32 v0, v97, v97
	v_max_f32_e32 v0, v10, v0
	v_max3_f32 v0, v0, v98, v99
	v_max3_f32 v0, v0, v100, v101
	v_max3_f32 v0, v0, v102, v103
	v_max3_f32 v0, v0, v104, v105
	s_waitcnt lgkmcnt(1)
	v_mfma_f32_32x32x16_bf16 v[48:63], v[2:5], v[136:139], v[48:63]
	v_max3_f32 v0, v0, v106, v107
	v_max3_f32 v0, v0, v108, v109
	v_max3_f32 v0, v0, v110, v111
	v_mov_b32_e32 v2, v0
	s_nop 1
	v_permlane32_swap_b32_e32 v0, v2
	s_waitcnt lgkmcnt(0)
	v_max_f32_e32 v2, v2, v2
	v_mfma_f32_32x32x16_bf16 v[48:63], v[6:9], v[132:135], v[48:63]
	v_max_f32_e32 v0, v0, v2
	v_cmp_ge_f32_e32 vcc, v0, v162
	s_cbranch_vccz .LBB0_305
	v_add_f32_e32 v2, 0x41000000, v167
	v_cmp_gt_f32_e32 vcc, v0, v2
	s_cbranch_vccz .LBB0_306
	v_max_f32_e32 v0, v0, v0
	v_max_f32_e32 v2, v167, v167
	v_max_f32_e32 v0, v2, v0
	s_and_saveexec_b64 s[78:79], s[74:75]
	s_cbranch_execz .LBB0_304
	v_sub_f32_e32 v2, v167, v0
	v_exp_f32_e32 v2, v2
	ds_write_b32 v73, v2

.LBB0_307:
	v_lshl_add_u32 v235, s17, 14, v78
	v_add_u32_e32 v234, v235, v76
	v_add_u32_e32 v235, v235, v77
	ds_read_b64_tr_b16 v[174:175], v234 offset:32768
	ds_read_b64_tr_b16 v[176:177], v234 offset:33792
	ds_read_b64_tr_b16 v[178:179], v235 offset:32768
	ds_read_b64_tr_b16 v[180:181], v235 offset:33792
	ds_read_b64_tr_b16 v[182:183], v234 offset:34816
	ds_read_b64_tr_b16 v[184:185], v234 offset:35840
	ds_read_b64_tr_b16 v[186:187], v235 offset:34816
	ds_read_b64_tr_b16 v[188:189], v235 offset:35840
	v_sub_f32_e32 v96, v96, v0
	v_sub_f32_e32 v97, v97, v0
	v_sub_f32_e32 v98, v98, v0
	v_sub_f32_e32 v99, v99, v0
	v_sub_f32_e32 v100, v100, v0
	v_sub_f32_e32 v101, v101, v0
	v_sub_f32_e32 v102, v102, v0
	v_sub_f32_e32 v103, v103, v0
	v_exp_f32_e32 v96, v96
	v_exp_f32_e32 v97, v97
	v_exp_f32_e32 v98, v98
	v_exp_f32_e32 v99, v99
	v_exp_f32_e32 v100, v100
	v_exp_f32_e32 v101, v101
	v_exp_f32_e32 v102, v102
	v_exp_f32_e32 v103, v103
	v_cvt_pk_bf16_f32 v196, v96, v97
	v_cvt_pk_bf16_f32 v197, v98, v99
	v_cvt_pk_bf16_f32 v198, v100, v101
	v_cvt_pk_bf16_f32 v199, v102, v103
	v_sub_f32_e32 v104, v104, v0
	v_sub_f32_e32 v105, v105, v0
	v_sub_f32_e32 v106, v106, v0
	v_sub_f32_e32 v107, v107, v0
	v_sub_f32_e32 v108, v108, v0
	v_sub_f32_e32 v109, v109, v0
	v_sub_f32_e32 v110, v110, v0
	v_sub_f32_e32 v111, v111, v0
	s_mov_b32 s77, s76
	s_mov_b32 s78, s76
	s_mov_b32 s79, s76
	s_movk_i32 s77, 0x110
	s_waitcnt lgkmcnt(6)
	v_mfma_f32_32x32x16_bf16 v[16:31], v[196:199], v[174:177], v[16:31]
	v_exp_f32_e32 v104, v104
	v_exp_f32_e32 v105, v105
	v_exp_f32_e32 v106, v106
	s_waitcnt lgkmcnt(4)
	v_mfma_f32_32x32x16_bf16 v[32:47], v[196:199], v[178:181], v[32:47]
	v_exp_f32_e32 v107, v107
	v_exp_f32_e32 v108, v108
	v_exp_f32_e32 v109, v109
	v_mfma_f32_32x32x16_bf16 v[80:95], v[196:199], v[190:193], v[80:95]
	v_exp_f32_e32 v110, v110
	v_exp_f32_e32 v111, v111
	v_cvt_pk_bf16_f32 v200, v104, v105
	v_cvt_pk_bf16_f32 v201, v106, v107
	v_cvt_pk_bf16_f32 v202, v108, v109
	v_cvt_pk_bf16_f32 v203, v110, v111
	s_nop 0
	s_waitcnt lgkmcnt(2)
	v_mfma_f32_32x32x16_bf16 v[16:31], v[200:203], v[182:185], v[16:31]
	s_waitcnt lgkmcnt(0)
	v_mfma_f32_32x32x16_bf16 v[32:47], v[200:203], v[186:189], v[32:47]
	v_mfma_f32_32x32x16_bf16 v[80:95], v[200:203], v[190:193], v[80:95]
.LBB0_308:
	s_add_i32 s5, s17, 1
	s_and_b32 s5, s5, 3
	v_lshl_add_u32 v10, s5, 13, v72
	s_or_b32 s22, s5, s95
	v_add_u32_e32 v2, v10, v165
	v_lshl_add_u32 v6, s22, 8, v75
	ds_read_b128 v[2:5], v2
	ds_read_b128 v[96:99], v6
	ds_read_b128 v[100:103], v6 offset:32
	ds_read_b128 v[104:107], v6 offset:64
	ds_read_b128 v[108:111], v6 offset:96
	v_add_u32_e32 v6, v10, v166
	ds_read_b128 v[6:9], v6
	s_waitcnt lgkmcnt(1)
	v_mfma_f32_32x32x16_bf16 v[96:111], v[2:5], v[128:131], v[96:111]
	v_add_u32_e32 v2, v10, v160
	ds_read_b128 v[2:5], v2
	v_max_f32_e32 v11, v48, v48
	s_waitcnt lgkmcnt(1)
	v_mfma_f32_32x32x16_bf16 v[96:111], v[6:9], v[140:143], v[96:111]
	v_add_u32_e32 v6, v10, v163
	ds_read_b128 v[6:9], v6
	v_max_f32_e32 v10, v49, v49
	v_max_f32_e32 v10, v11, v10
	v_max3_f32 v10, v10, v50, v51
	v_max3_f32 v10, v10, v52, v53
	s_waitcnt lgkmcnt(1)
	v_mfma_f32_32x32x16_bf16 v[96:111], v[2:5], v[136:139], v[96:111]
	v_max3_f32 v2, v10, v54, v55
	v_max3_f32 v2, v2, v56, v57
	v_max3_f32 v2, v2, v58, v59
	v_max3_f32 v2, v2, v60, v61
	v_max3_f32 v2, v2, v62, v63
	v_mov_b32_e32 v3, v2
	s_nop 1
	v_permlane32_swap_b32_e32 v2, v3
	s_waitcnt lgkmcnt(0)
	v_max_f32_e32 v3, v3, v3
	v_mfma_f32_32x32x16_bf16 v[96:111], v[6:9], v[132:135], v[96:111]
	v_max_f32_e32 v2, v2, v3
	v_cmp_ge_f32_e32 vcc, v2, v162
	s_cbranch_vccz .LBB0_313
	v_add_f32_e32 v3, 0x41000000, v0
	v_cmp_gt_f32_e32 vcc, v2, v3
	s_cbranch_vccz .LBB0_314
	v_max_f32_e32 v2, v2, v2
	v_max_f32_e32 v3, v0, v0
	v_max_f32_e32 v167, v3, v2
	s_and_saveexec_b64 s[78:79], s[74:75]
	s_cbranch_execz .LBB0_312
	v_sub_f32_e32 v0, v0, v167
	v_exp_f32_e32 v0, v0
	ds_write_b32 v73, v0

.LBB0_315:
	v_lshl_add_u32 v235, s17, 14, v79
	v_add_u32_e32 v234, v235, v76
	v_add_u32_e32 v235, v235, v77
	ds_read_b64_tr_b16 v[174:175], v234 offset:32768
	ds_read_b64_tr_b16 v[176:177], v234 offset:33792
	ds_read_b64_tr_b16 v[178:179], v235 offset:32768
	ds_read_b64_tr_b16 v[180:181], v235 offset:33792
	ds_read_b64_tr_b16 v[182:183], v234 offset:34816
	ds_read_b64_tr_b16 v[184:185], v234 offset:35840
	ds_read_b64_tr_b16 v[186:187], v235 offset:34816
	ds_read_b64_tr_b16 v[188:189], v235 offset:35840
	v_sub_f32_e32 v48, v48, v167
	v_sub_f32_e32 v49, v49, v167
	v_sub_f32_e32 v50, v50, v167
	v_sub_f32_e32 v51, v51, v167
	v_sub_f32_e32 v52, v52, v167
	v_sub_f32_e32 v53, v53, v167
	v_sub_f32_e32 v54, v54, v167
	v_sub_f32_e32 v55, v55, v167
	v_exp_f32_e32 v48, v48
	v_exp_f32_e32 v49, v49
	v_exp_f32_e32 v50, v50
	v_exp_f32_e32 v51, v51
	v_exp_f32_e32 v52, v52
	v_exp_f32_e32 v53, v53
	v_exp_f32_e32 v54, v54
	v_exp_f32_e32 v55, v55
	v_cvt_pk_bf16_f32 v196, v48, v49
	v_cvt_pk_bf16_f32 v197, v50, v51
	v_cvt_pk_bf16_f32 v198, v52, v53
	v_cvt_pk_bf16_f32 v199, v54, v55
	v_sub_f32_e32 v56, v56, v167
	v_sub_f32_e32 v57, v57, v167
	v_sub_f32_e32 v58, v58, v167
	v_sub_f32_e32 v59, v59, v167
	v_sub_f32_e32 v60, v60, v167
	v_sub_f32_e32 v61, v61, v167
	v_sub_f32_e32 v62, v62, v167
	v_sub_f32_e32 v63, v63, v167
	s_mov_b32 s77, s76
	s_mov_b32 s78, s76
	s_mov_b32 s79, s76
	s_movk_i32 s77, 0x110
	s_waitcnt lgkmcnt(6)
	v_mfma_f32_32x32x16_bf16 v[16:31], v[196:199], v[174:177], v[16:31]
	v_exp_f32_e32 v56, v56
	v_exp_f32_e32 v57, v57
	v_exp_f32_e32 v58, v58
	s_waitcnt lgkmcnt(4)
	v_mfma_f32_32x32x16_bf16 v[32:47], v[196:199], v[178:181], v[32:47]
	v_exp_f32_e32 v59, v59
	v_exp_f32_e32 v60, v60
	v_exp_f32_e32 v61, v61
	v_mfma_f32_32x32x16_bf16 v[80:95], v[196:199], v[190:193], v[80:95]
	v_exp_f32_e32 v62, v62
	v_exp_f32_e32 v63, v63
	v_cvt_pk_bf16_f32 v200, v56, v57
	v_cvt_pk_bf16_f32 v201, v58, v59
	v_cvt_pk_bf16_f32 v202, v60, v61
	v_cvt_pk_bf16_f32 v203, v62, v63
	s_nop 0
	s_waitcnt lgkmcnt(2)
	v_mfma_f32_32x32x16_bf16 v[16:31], v[200:203], v[182:185], v[16:31]
	s_waitcnt lgkmcnt(0)
	v_mfma_f32_32x32x16_bf16 v[32:47], v[200:203], v[186:189], v[32:47]
	v_mfma_f32_32x32x16_bf16 v[80:95], v[200:203], v[190:193], v[80:95]
	s_mov_b64 s[78:79], -1
	s_and_b64 vcc, exec, s[90:91]
	s_cbranch_vccz .LBB0_317
